# lazy conversion: cached K/V rows of the sample streams converted f32->bf16 inside stick-breaking attention only for visited key blocks; the two 50 MB up-front conversion loops in P0 removed
# speedup vs baseline: 1.2420x; 1.0126x over previous
.LBB0_136:
	s_or_b64 exec, exec, s[0:1]
	s_waitcnt lgkmcnt(0)
	s_add_u32 s30, s50, 0x16f80000
	s_mov_b64 s[0:1], 0x300000
	s_addc_u32 s31, s51, 0
	v_cmp_gt_u64_e32 vcc, s[0:1], v[6:7]
	s_and_saveexec_b64 s[4:5], vcc
	s_branch .LBB0_139
	s_mov_b32 s35, 0
	s_lshl_b64 s[6:7], s[34:35], 9
	s_mov_b64 s[10:11], 0
	s_mov_b32 s33, 0xaaaaaaab
	v_mov_b32_e32 v5, 0
	s_mov_b32 s35, 0x600000
	v_mov_b64_e32 v[8:9], s[20:21]
	s_mov_b32 s38, 0x30c000
	v_mov_b64_e32 v[10:11], s[30:31]
	s_mov_b64 s[20:21], 0x2fffff
	v_mov_b64_e32 v[12:13], v[6:7]

.LBB0_139:
	s_or_b64 exec, exec, s[4:5]
	s_add_u32 s20, s50, 0x187e0000
	s_addc_u32 s21, s51, 0
	s_and_saveexec_b64 s[0:1], vcc
	s_branch .LBB0_142
	s_mov_b32 s35, 0
	s_lshl_b64 s[4:5], s[34:35], 9
	s_mov_b64 s[6:7], 0
	s_mov_b32 s33, 0xaaaaaaab
	v_mov_b32_e32 v5, 0
	s_mov_b32 s35, 0x600000
	v_mov_b64_e32 v[8:9], s[22:23]
	s_mov_b32 s22, 0x30c000
	v_mov_b64_e32 v[10:11], s[20:21]
	s_mov_b64 s[10:11], 0x2fffff
	v_mov_b64_e32 v[12:13], v[6:7]

.LBB0_869:
	s_or_b64 exec, exec, s[52:53]
	s_add_u32 s46, s50, s46
	s_addc_u32 s47, s51, s47
	s_lshl_b64 s[44:45], s[44:45], 1
	s_add_u32 s44, s46, s44
	s_addc_u32 s45, s47, s45
	s_lshl_b64 s[22:23], s[22:23], 1
	s_add_u32 s22, s44, s22
	s_addc_u32 s23, s45, s23
	s_add_i32 s44, s60, s61
	s_add_i32 s45, s44, -2
	s_lshr_b32 s45, s45, 6
	s_cmp_gt_i32 s44, 1
	s_cselect_b32 s46, s45, 0
	s_lshl_b32 s60, s46, 6
	v_or_b32_e32 v16, s60, v234
	v_min_u32_e32 v16, s40, v16
	v_mul_u32_u24_e32 v16, 0x600, v16
	v_lshl_add_u64 v[74:75], s[18:19], 0, v[68:69]
	v_lshl_add_u64 v[76:77], s[22:23], 0, v[68:69]
	v_lshlrev_b32_e32 v16, 1, v16
	v_mov_b32_e32 v17, v69
	v_lshl_add_u64 v[18:19], v[74:75], 0, v[16:17]
	v_lshl_add_u64 v[16:17], v[76:77], 0, v[16:17]
	global_load_dwordx4 v[52:55], v[16:17], off
	v_add_u32_e32 v16, s60, v83
	v_min_u32_e32 v16, s40, v16
	v_mul_u32_u24_e32 v16, 0x600, v16
	v_lshlrev_b32_e32 v16, 1, v16
	v_mov_b32_e32 v17, v69
	global_load_dwordx4 v[48:51], v[18:19], off
	v_lshl_add_u64 v[18:19], v[74:75], 0, v[16:17]
	v_lshl_add_u64 v[16:17], v[76:77], 0, v[16:17]
	global_load_dwordx4 v[56:59], v[18:19], off
	global_load_dwordx4 v[60:63], v[16:17], off
	v_add_u32_e32 v16, s61, v237
	v_or_b32_e32 v78, v16, v198
	v_mov_b32_e32 v97, 0
	v_or_b32_e32 v96, 15, v16
	v_mov_b32_e32 v73, v78
	s_mov_b64 s[44:45], 0
	v_mov_b32_e32 v98, s46
	v_mov_b32_e32 v44, 0
	v_mov_b32_e32 v45, v97
	v_mov_b32_e32 v46, v97
	v_mov_b32_e32 v47, v97
	v_mov_b32_e32 v40, 0
	v_mov_b32_e32 v41, v97
	v_mov_b32_e32 v42, v97
	v_mov_b32_e32 v43, v97
	v_mov_b32_e32 v36, 0
	v_mov_b32_e32 v37, v97
	v_mov_b32_e32 v38, v97
	v_mov_b32_e32 v39, v97
	v_mov_b32_e32 v32, 0
	v_mov_b32_e32 v33, v97
	v_mov_b32_e32 v34, v97
	v_mov_b32_e32 v35, v97
	v_mov_b32_e32 v28, 0
	v_mov_b32_e32 v29, v97
	v_mov_b32_e32 v30, v97
	v_mov_b32_e32 v31, v97
	v_mov_b32_e32 v24, 0
	v_mov_b32_e32 v25, v97
	v_mov_b32_e32 v26, v97
	v_mov_b32_e32 v27, v97
	v_mov_b32_e32 v20, 0
	v_mov_b32_e32 v21, v97
	v_mov_b32_e32 v22, v97
	v_mov_b32_e32 v23, v97
	v_mov_b32_e32 v16, 0
	v_mov_b32_e32 v17, v97
	v_mov_b32_e32 v18, v97
	v_mov_b32_e32 v19, v97
	s_mov_b32 s101, 0
	s_branch .LBB0_871

.LBB0_871:
	v_add_u32_e32 v64, v88, v79
	s_barrier
	s_cmp_eq_u32 s101, 0
	s_cbranch_scc1 .Lsb_nocvt
	s_waitcnt vmcnt(0)
	v_cvt_pk_bf16_f32 v48, v160, v161
	v_cvt_pk_bf16_f32 v49, v162, v163
	v_cvt_pk_bf16_f32 v50, v164, v165
	v_cvt_pk_bf16_f32 v51, v166, v167
	v_cvt_pk_bf16_f32 v52, v168, v169
	v_cvt_pk_bf16_f32 v53, v170, v171
	v_cvt_pk_bf16_f32 v54, v172, v173
	v_cvt_pk_bf16_f32 v55, v174, v175
	v_cvt_pk_bf16_f32 v56, v176, v177
	v_cvt_pk_bf16_f32 v57, v178, v179
	v_cvt_pk_bf16_f32 v58, v180, v181
	v_cvt_pk_bf16_f32 v59, v182, v183
	v_cvt_pk_bf16_f32 v60, v184, v185
	v_cvt_pk_bf16_f32 v61, v186, v187
	v_cvt_pk_bf16_f32 v62, v188, v189
	v_cvt_pk_bf16_f32 v63, v190, v191
	s_mov_b32 s101, 0
.Lsb_nocvt:
	s_waitcnt vmcnt(2)
	ds_write_b128 v64, v[48:51]
	v_add_u32_e32 v64, v88, v80
	ds_write_b128 v64, v[52:55] offset:17408
	v_add_u32_e32 v64, v88, v82
	v_cmp_gt_i32_e32 vcc, 1, v98
	s_waitcnt vmcnt(1)
	ds_write_b128 v64, v[56:59]
	v_add_u32_e32 v64, v88, v81
	s_and_b64 vcc, exec, vcc
	s_waitcnt vmcnt(0)
	ds_write_b128 v64, v[60:63] offset:17408
	s_waitcnt lgkmcnt(0)
	s_barrier
	s_cbranch_vccnz .LBB0_873
	s_cmp_lg_u32 s40, 0x40f
	s_cbranch_scc1 .Lsb_bf16
	s_sub_u32 s100, s94, 0xf0
	s_subb_u32 s101, s95, 0
	s_load_dwordx4 s[96:99], s[100:101], 0x0
	s_and_b32 s100, s57, 0xff
	s_mulk_i32 s100, 0xab
	s_lshr_b32 s100, s100, 11
	s_mul_i32 s100, s100, 0x600000
	s_lshl_b32 s101, s58, 9
	s_add_u32 s100, s100, s101
	v_add_u32_e32 v192, s60, v92
	v_mul_u32_u24_e32 v192, 0x1800, v192
	v_lshl_add_u32 v192, v68, 1, v192
	v_add_u32_e32 v193, 0x30000, v192
	s_waitcnt lgkmcnt(0)
	s_add_u32 s96, s96, s100
	s_addc_u32 s97, s97, 0
	s_add_u32 s98, s98, s100
	s_addc_u32 s99, s99, 0
	global_load_dwordx4 v[160:163], v192, s[96:97]
	global_load_dwordx4 v[164:167], v192, s[96:97] offset:16
	global_load_dwordx4 v[168:171], v192, s[98:99]
	global_load_dwordx4 v[172:175], v192, s[98:99] offset:16
	global_load_dwordx4 v[176:179], v193, s[96:97]
	global_load_dwordx4 v[180:183], v193, s[96:97] offset:16
	global_load_dwordx4 v[184:187], v193, s[98:99]
	global_load_dwordx4 v[188:191], v193, s[98:99] offset:16
	s_mov_b32 s101, 1
	s_branch .LBB0_873
.Lsb_bf16:
	v_add_u32_e32 v48, s60, v92
	v_add_u32_e32 v56, s60, v91
	v_min_i32_e32 v52, s40, v48
	v_min_i32_e32 v60, s40, v56
	v_mad_u64_u32 v[48:49], s[18:19], v52, s35, v[74:75]
	v_mad_u64_u32 v[52:53], s[18:19], v52, s35, v[76:77]
	v_mad_u64_u32 v[56:57], s[18:19], v60, s35, v[74:75]
	v_mad_u64_u32 v[60:61], s[18:19], v60, s35, v[76:77]
	global_load_dwordx4 v[48:51], v[48:49], off
	s_nop 0
	global_load_dwordx4 v[52:55], v[52:53], off
	s_nop 0
	global_load_dwordx4 v[56:59], v[56:57], off
	s_nop 0
	global_load_dwordx4 v[60:63], v[60:61], off
